# stack: LRU c-read hoist + const folding + GEMM first-K-step srcC=0 peel on top of v13
# speedup vs baseline: 1.0186x; 1.0186x over previous
; __device__ __forceinline__ unsigned cvt_pk_bf16(float lo, float hi) { unsigned r; asm volatile("v_cvt_pk_bf16_f32 %0, %1, %2" : "=v"(r) : "v"(lo), "v"(hi)); return r; }
; __device__ __forceinline__ float bflo(unsigned w) { return __uint_as_float(w << 16); }
; __device__ __forceinline__ float bfhi(unsigned w) { return __uint_as_float(w & 0xffff0000u); }
; __device__ void lru_fused_phase(const int bid, const int nblk, bf16_t* __restrict__ U, bf16_t* __restrict__ HF, const bf16_t* __restrict__ Wg, const float* __restrict__ cw, const float* __restrict__ cb, ...
;     ...
;             const float ba = b_a[e * DRNN + ch], bi_ = b_i[e * DRNN + ch], sp = c8sp[e * DRNN + ch];
;             float hs = 0.f;
;             unsigned xr[11];
;             {
;                 const int k = e == 0 ? 0 : 31; const int p0 = 64 * k + 8 * wid - 2;
; #pragma unroll
;                 for (int i = 0; i < 11; ++i) { const int pos = p0 + i; xr[i] = (pos >= 0 && pos < SEQ) ? *(const unsigned*)(recp + (long)pos * (2 * DRNN)) : 0u; }
; #pragma unroll
;                 for (int r = 0; r < 8; ++r) {
;                     const float c0 = wb[0] + w0[0] * bflo(xr[r]) + w1[0] * bflo(xr[r + 1]) + w2[0] * bflo(xr[r + 2]) + w3[0] * bflo(xr[r + 3]);
;                     const float c1 = wb[1] + w0[1] * bfhi(xr[r]) + w1[1] * bfhi(xr[r + 1]) + w2[1] * bfhi(xr[r + 2]) + w3[1] * bfhi(xr[r + 3]);
;                     *(unsigned*)(smem + (8 * wid + r) * RS + lane * 4) = cvt_pk_bf16(c0, c1);
;                 }
;             }
;             __syncthreads();
.LBB0_91:
	s_or_b64 exec, exec, s[2:3]
	s_waitcnt vmcnt(0)
	v_mul_f32_e32 v157, 0xbfb8aa3b, v82
	v_mul_f32_e32 v127, 0xbfb8aa3b, v83
	v_mul_f32_e32 v160, 0xbfb8aa3b, v86
	v_lshlrev_b32_e32 v10, 16, v87
	v_fma_f32 v10, v48, v10, v56
	v_lshlrev_b32_e32 v36, 16, v88
	v_and_b32_e32 v39, 0xffff0000, v87
	v_fmac_f32_e32 v10, v50, v36
	v_lshlrev_b32_e32 v37, 16, v89
	v_fma_f32 v39, v49, v39, v57
	v_and_b32_e32 v40, 0xffff0000, v88
	v_fmac_f32_e32 v10, v52, v37
	v_lshlrev_b32_e32 v38, 16, v90
	v_fmac_f32_e32 v39, v51, v40
	v_and_b32_e32 v41, 0xffff0000, v89
	v_fmac_f32_e32 v10, v54, v38
	v_fmac_f32_e32 v39, v53, v41
	v_and_b32_e32 v42, 0xffff0000, v90
	v_fmac_f32_e32 v39, v55, v42
	v_cvt_pk_bf16_f32 v10, v10, v39
	ds_write_b32 v75, v10
	v_fma_f32 v10, v48, v36, v56
	v_fmac_f32_e32 v10, v50, v37
	v_fma_f32 v39, v49, v40, v57
	v_fmac_f32_e32 v10, v52, v38
	v_lshlrev_b32_e32 v36, 16, v92
	v_fmac_f32_e32 v39, v51, v41
	v_fmac_f32_e32 v10, v54, v36
	v_fmac_f32_e32 v39, v53, v42
	v_and_b32_e32 v40, 0xffff0000, v92
	v_fmac_f32_e32 v39, v55, v40
	v_cvt_pk_bf16_f32 v10, v10, v39
	ds_write_b32 v75, v10 offset:272
	v_fma_f32 v10, v48, v37, v56
	v_fmac_f32_e32 v10, v50, v38
	v_fma_f32 v39, v49, v41, v57
	v_fmac_f32_e32 v10, v52, v36
	v_lshlrev_b32_e32 v37, 16, v93
	v_fmac_f32_e32 v39, v51, v42
	v_fmac_f32_e32 v10, v54, v37
	v_fmac_f32_e32 v39, v53, v40
	v_and_b32_e32 v41, 0xffff0000, v93
	v_fmac_f32_e32 v39, v55, v41
	v_cvt_pk_bf16_f32 v10, v10, v39
	ds_write_b32 v75, v10 offset:544
	v_fma_f32 v10, v48, v38, v56
	v_fmac_f32_e32 v10, v50, v36
	v_fma_f32 v39, v49, v42, v57
	v_fmac_f32_e32 v10, v52, v37
	v_lshlrev_b32_e32 v38, 16, v94
	v_fmac_f32_e32 v39, v51, v40
	v_fmac_f32_e32 v10, v54, v38
	v_fmac_f32_e32 v39, v53, v41
	v_and_b32_e32 v42, 0xffff0000, v94
	v_fmac_f32_e32 v39, v55, v42
	v_cvt_pk_bf16_f32 v10, v10, v39
	ds_write_b32 v75, v10 offset:816
	v_fma_f32 v10, v48, v36, v56
	v_fmac_f32_e32 v10, v50, v37
	v_fma_f32 v39, v49, v40, v57
	v_fmac_f32_e32 v10, v52, v38
	v_lshlrev_b32_e32 v36, 16, v95
	v_fmac_f32_e32 v39, v51, v41
	v_fmac_f32_e32 v10, v54, v36
	v_fmac_f32_e32 v39, v53, v42
	v_and_b32_e32 v40, 0xffff0000, v95
	v_fmac_f32_e32 v39, v55, v40
	v_cvt_pk_bf16_f32 v10, v10, v39
	ds_write_b32 v75, v10 offset:1088
	v_fma_f32 v10, v48, v37, v56
	v_fmac_f32_e32 v10, v50, v38
	v_fma_f32 v39, v49, v41, v57
	v_fmac_f32_e32 v10, v52, v36
	v_lshlrev_b32_e32 v37, 16, v96
	v_fmac_f32_e32 v39, v51, v42
	v_fmac_f32_e32 v10, v54, v37
	v_fmac_f32_e32 v39, v53, v40
	v_and_b32_e32 v41, 0xffff0000, v96
	v_fmac_f32_e32 v39, v55, v41
	v_cvt_pk_bf16_f32 v10, v10, v39
	ds_write_b32 v75, v10 offset:1360
	v_fma_f32 v10, v48, v38, v56
	v_fmac_f32_e32 v10, v50, v36
	v_fma_f32 v39, v49, v42, v57
	v_fmac_f32_e32 v10, v52, v37
	v_lshlrev_b32_e32 v38, 16, v97
	v_fmac_f32_e32 v39, v51, v40
	v_fmac_f32_e32 v10, v54, v38
	v_fmac_f32_e32 v39, v53, v41
	v_and_b32_e32 v42, 0xffff0000, v97
	v_fmac_f32_e32 v39, v55, v42
	v_cvt_pk_bf16_f32 v10, v10, v39
	ds_write_b32 v75, v10 offset:1632
	v_fma_f32 v10, v48, v36, v56
	v_fmac_f32_e32 v10, v50, v37
	v_fmac_f32_e32 v10, v52, v38
	v_lshlrev_b32_e32 v36, 16, v103
	v_fmac_f32_e32 v10, v54, v36
	v_fma_f32 v36, v49, v40, v57
	s_xor_b64 s[64:65], s[60:61], -1
	v_fmac_f32_e32 v36, v51, v41
	v_fmac_f32_e32 v36, v53, v42
	v_and_b32_e32 v37, 0xffff0000, v103
	s_and_b64 s[2:3], s[60:61], exec
	v_fmac_f32_e32 v36, v55, v37
	v_cvt_pk_bf16_f32 v10, v10, v36
	s_cselect_b32 s70, 0, 48
	ds_write_b32 v75, v10 offset:1904
	v_or_b32_e32 v10, s70, v47
	v_mul_u32_u24_e32 v98, 0x110, v10
	v_or_b32_e32 v10, s70, v46
	v_mul_u32_u24_e32 v99, 0x110, v10
	v_or_b32_e32 v100, 64, v76
	v_or_b32_e32 v101, 0x80, v76
	v_or_b32_e32 v102, 0xc0, v76
	v_mov_b32_e32 v105, 0
	s_mov_b32 s71, 30
	s_mov_b32 s72, 1
	s_waitcnt lgkmcnt(0)
	s_barrier
	s_branch .LBB0_93

; __device__ __forceinline__ float bf2f(bf16_t b) { return __uint_as_float(((unsigned)b) << 16); }
; __device__ __forceinline__ float sigmoidf(float z) { return __builtin_amdgcn_rcpf(1.0f + __expf(-z)); }
; __device__ void lru_fused_phase(const int bid, const int nblk, bf16_t* __restrict__ U, bf16_t* __restrict__ HF, const bf16_t* __restrict__ Wg, const float* __restrict__ cw, const float* __restrict__ cb, ...
;     ...
; #pragma unroll
;                     for (int j = 0; j < 4; ++j) {
;                         const float c = bf2f(*(const unsigned short*)(buf + (16 * rt + 4 * fq + j) * RS + chl * 2));
;                         const float r = sigmoidf(za[j] + ba), ig = sigmoidf(zi[j] + bi_);
;                         const float la = -sp * r;
;                         av[j] = __expf(la);
;                         bv[j] = __builtin_sqrtf(fmaxf(1.0f - av[j] * av[j], 0.f)) * ig * c;
;                     }
.LBB0_119:
	s_bitcmp1_b32 s2, 0
	s_cselect_b32 s2, 0x4400, 0
	s_add_i32 s2, s2, 0
	v_add_u32_e32 v104, s2, v8
	v_add_u32_e32 v106, v104, v98
	ds_read_b128 v[36:39], v106
	ds_read_b128 v[108:111], v106 offset:64
	v_add_u32_e32 v10, s2, v74
	s_mov_b64 s[2:3], -1
	s_waitcnt lgkmcnt(1)
	v_mfma_f32_16x16x32_bf16 v[40:43], v[36:39], v[0:3], 0
	v_mfma_f32_16x16x32_bf16 v[36:39], v[36:39], v[20:23], 0
	s_waitcnt lgkmcnt(0)
	v_mfma_f32_16x16x32_bf16 v[40:43], v[108:111], v[4:7], v[40:43]
	v_mfma_f32_16x16x32_bf16 v[36:39], v[108:111], v[24:27], v[36:39]
	ds_read_b128 v[108:111], v106 offset:128
	s_waitcnt lgkmcnt(0)
	v_mfma_f32_16x16x32_bf16 v[40:43], v[108:111], v[12:15], v[40:43]
	v_mfma_f32_16x16x32_bf16 v[36:39], v[108:111], v[28:31], v[36:39]
	ds_read_b128 v[108:111], v106 offset:192
	v_add_u32_e32 v106, v10, v99
	s_waitcnt lgkmcnt(0)
	v_mfma_f32_16x16x32_bf16 v[40:43], v[108:111], v[16:19], v[40:43]
	s_nop 7
	ds_read_u16 v153, v106
	ds_read_u16 v154, v106 offset:272
	ds_read_u16 v155, v106 offset:544
	ds_read_u16 v156, v106 offset:816
	v_fmamk_f32 v40, v40, 0xbfb8aa3b, v157
	v_mfma_f32_16x16x32_bf16 v[36:39], v[108:111], v[32:35], v[36:39]
	v_or_b32_e32 v152, s70, v47
	v_xor_b32_e32 v152, 16, v152
	v_mad_u32_u24 v152, v152, s35, v104
	ds_read_b128 v[128:131], v152
	ds_read_b128 v[132:135], v152 offset:64
	ds_read_b128 v[136:139], v152 offset:128
	ds_read_b128 v[140:143], v152 offset:192
	v_exp_f32_e32 v40, v40
	v_fmamk_f32 v41, v41, 0xbfb8aa3b, v157
	v_exp_f32_e32 v41, v41
	s_nop 2
	v_fmamk_f32 v36, v36, 0xbfb8aa3b, v127
	v_add_f32_e32 v40, 1.0, v40
	v_exp_f32_e32 v36, v36
	v_rcp_f32_e32 v40, v40
	v_fmamk_f32 v37, v37, 0xbfb8aa3b, v127
	v_add_f32_e32 v36, 1.0, v36
	v_rcp_f32_e32 v109, v36
	v_mul_f32_e32 v36, v40, v160
	v_exp_f32_e32 v36, v36
	v_add_f32_e32 v41, 1.0, v41
	v_exp_f32_e32 v37, v37
	v_rcp_f32_e32 v41, v41
	v_fma_f32 v40, -v36, v36, 1.0
	v_max_f32_e32 v40, 0, v40
	v_add_f32_e32 v37, 1.0, v37
	v_sqrt_f32_e32 v40, v40
	s_nop 0
	v_fmamk_f32 v42, v42, 0xbfb8aa3b, v157
	v_exp_f32_e32 v42, v42
	v_fmamk_f32 v38, v38, 0xbfb8aa3b, v127
	v_add_f32_e32 v42, 1.0, v42
	v_exp_f32_e32 v38, v38
	v_rcp_f32_e32 v42, v42
	v_mul_f32_e32 v40, v109, v40
	v_rcp_f32_e32 v109, v37
	v_mul_f32_e32 v37, v41, v160
	v_exp_f32_e32 v37, v37
	v_add_f32_e32 v38, 1.0, v38
	v_fmamk_f32 v43, v43, 0xbfb8aa3b, v157
	v_fma_f32 v41, -v37, v37, 1.0
	v_max_f32_e32 v41, 0, v41
	s_waitcnt lgkmcnt(0)
	v_lshlrev_b32_e32 v108, 16, v153
	v_sqrt_f32_e32 v41, v41
	s_nop 0
	v_mul_f32_e32 v40, v40, v108
	v_exp_f32_e32 v43, v43
	s_waitcnt lgkmcnt(0)
	v_lshlrev_b32_e32 v108, 16, v154
	v_fmamk_f32 v39, v39, 0xbfb8aa3b, v127
	s_waitcnt lgkmcnt(0)
	v_mfma_f32_16x16x32_bf16 v[144:147], v[128:131], v[0:3], 0
	v_mfma_f32_16x16x32_bf16 v[148:151], v[128:131], v[20:23], 0
	v_mfma_f32_16x16x32_bf16 v[144:147], v[132:135], v[4:7], v[144:147]
	v_mfma_f32_16x16x32_bf16 v[148:151], v[132:135], v[24:27], v[148:151]
	v_mfma_f32_16x16x32_bf16 v[144:147], v[136:139], v[12:15], v[144:147]
	v_mfma_f32_16x16x32_bf16 v[148:151], v[136:139], v[28:31], v[148:151]
	v_mfma_f32_16x16x32_bf16 v[144:147], v[140:143], v[16:19], v[144:147]
	v_mfma_f32_16x16x32_bf16 v[148:151], v[140:143], v[32:35], v[148:151]
	v_add_f32_e32 v43, 1.0, v43
	v_mul_f32_e32 v41, v109, v41
	v_rcp_f32_e32 v109, v38
	v_mul_f32_e32 v38, v42, v160
	v_exp_f32_e32 v38, v38
	v_mul_f32_e32 v41, v41, v108
	v_exp_f32_e32 v39, v39
	v_fma_f32 v42, -v38, v38, 1.0
	v_max_f32_e32 v42, 0, v42
	v_rcp_f32_e32 v43, v43
	v_sqrt_f32_e32 v42, v42
	s_nop 0
	s_waitcnt lgkmcnt(0)
	v_lshlrev_b32_e32 v108, 16, v155
	v_add_f32_e32 v39, 1.0, v39
	s_waitcnt lgkmcnt(0)
	v_lshlrev_b32_e32 v106, 16, v156
	s_nop 1
	s_nop 1
	v_mul_f32_e32 v42, v109, v42
	v_mul_f32_e32 v42, v42, v108
	v_rcp_f32_e32 v108, v39
	v_mul_f32_e32 v39, v43, v160
	v_exp_f32_e32 v39, v39
	s_nop 0
	v_fma_f32 v43, -v39, v39, 1.0
	v_max_f32_e32 v43, 0, v43
	s_nop 0
	v_sqrt_f32_e32 v43, v43
	s_nop 0
	s_nop 0
	s_nop 0
	s_nop 1
	s_nop 1
	v_mul_f32_e32 v43, v108, v43
	v_mul_f32_e32 v43, v43, v106
	s_and_b64 vcc, exec, s[64:65]
	s_cbranch_vccz .LBB0_121
	v_fma_f32 v108, v38, v43, v42
	v_mul_f32_e32 v109, v38, v39
	v_fma_f32 v111, v37, v108, v41
	v_mul_f32_e32 v110, v37, v109
	v_fma_f32 v112, v36, v111, v40
	v_mul_f32_e32 v106, v36, v110
	s_mov_b64 s[2:3], 0

; __device__ __forceinline__ float bf2f(bf16_t b) { return __uint_as_float(((unsigned)b) << 16); }
; __device__ __forceinline__ float sigmoidf(float z) { return __builtin_amdgcn_rcpf(1.0f + __expf(-z)); }
; __device__ void lru_fused_phase(const int bid, const int nblk, bf16_t* __restrict__ U, bf16_t* __restrict__ HF, const bf16_t* __restrict__ Wg, const float* __restrict__ cw, const float* __restrict__ cb, ...
;     ...
; #pragma unroll
;                     for (int j = 0; j < 4; ++j) {
;                         const float c = bf2f(*(const unsigned short*)(buf + (16 * rt + 4 * fq + j) * RS + chl * 2));
;                         const float r = sigmoidf(za[j] + ba), ig = sigmoidf(zi[j] + bi_);
;                         const float la = -sp * r;
;                         av[j] = __expf(la);
;                         bv[j] = __builtin_sqrtf(fmaxf(1.0f - av[j] * av[j], 0.f)) * ig * c;
;                     }
.LBB0_142:
	s_mov_b64 s[2:3], -1
	s_waitcnt lgkmcnt(1)
	s_waitcnt lgkmcnt(0)
	s_waitcnt lgkmcnt(0)
	v_or_b32_e32 v105, s38, v46
	v_mad_u32_u24 v105, v105, s35, v10
	s_waitcnt lgkmcnt(0)
	v_or_b32_e32 v152, s70, v47
	v_xor_b32_e32 v152, 32, v152
	v_mad_u32_u24 v152, v152, s35, v104
	ds_read_b128 v[128:131], v152
	ds_read_b128 v[132:135], v152 offset:64
	ds_read_b128 v[136:139], v152 offset:128
	ds_read_b128 v[140:143], v152 offset:192
	ds_read_u16 v153, v105
	ds_read_u16 v154, v105 offset:272
	ds_read_u16 v155, v105 offset:544
	ds_read_u16 v156, v105 offset:816
	v_fmamk_f32 v40, v144, 0xbfb8aa3b, v157
	v_exp_f32_e32 v40, v40
	v_fmamk_f32 v41, v145, 0xbfb8aa3b, v157
	v_exp_f32_e32 v41, v41
	s_nop 2
	v_fmamk_f32 v36, v148, 0xbfb8aa3b, v127
	v_add_f32_e32 v40, 1.0, v40
	v_exp_f32_e32 v36, v36
	v_rcp_f32_e32 v40, v40
	v_fmamk_f32 v37, v149, 0xbfb8aa3b, v127
	v_add_f32_e32 v36, 1.0, v36
	v_rcp_f32_e32 v109, v36
	v_mul_f32_e32 v36, v40, v160
	v_exp_f32_e32 v36, v36
	v_add_f32_e32 v41, 1.0, v41
	v_exp_f32_e32 v37, v37
	v_rcp_f32_e32 v41, v41
	v_fma_f32 v40, -v36, v36, 1.0
	v_max_f32_e32 v40, 0, v40
	v_add_f32_e32 v37, 1.0, v37
	v_sqrt_f32_e32 v40, v40
	s_nop 0
	v_fmamk_f32 v42, v146, 0xbfb8aa3b, v157
	v_exp_f32_e32 v42, v42
	v_fmamk_f32 v38, v150, 0xbfb8aa3b, v127
	v_add_f32_e32 v42, 1.0, v42
	v_exp_f32_e32 v38, v38
	v_rcp_f32_e32 v42, v42
	v_mul_f32_e32 v40, v109, v40
	v_rcp_f32_e32 v109, v37
	v_mul_f32_e32 v37, v41, v160
	v_exp_f32_e32 v37, v37
	v_add_f32_e32 v38, 1.0, v38
	v_fmamk_f32 v43, v147, 0xbfb8aa3b, v157
	v_fma_f32 v41, -v37, v37, 1.0
	v_max_f32_e32 v41, 0, v41
	s_waitcnt lgkmcnt(0)
	v_lshlrev_b32_e32 v108, 16, v153
	v_sqrt_f32_e32 v41, v41
	s_nop 0
	v_mul_f32_e32 v40, v40, v108
	v_exp_f32_e32 v43, v43
	s_waitcnt lgkmcnt(0)
	v_lshlrev_b32_e32 v108, 16, v154
	v_fmamk_f32 v39, v151, 0xbfb8aa3b, v127
	s_waitcnt lgkmcnt(0)
	v_mfma_f32_16x16x32_bf16 v[144:147], v[128:131], v[0:3], 0
	v_mfma_f32_16x16x32_bf16 v[148:151], v[128:131], v[20:23], 0
	v_mfma_f32_16x16x32_bf16 v[144:147], v[132:135], v[4:7], v[144:147]
	v_mfma_f32_16x16x32_bf16 v[148:151], v[132:135], v[24:27], v[148:151]
	v_mfma_f32_16x16x32_bf16 v[144:147], v[136:139], v[12:15], v[144:147]
	v_mfma_f32_16x16x32_bf16 v[148:151], v[136:139], v[28:31], v[148:151]
	v_mfma_f32_16x16x32_bf16 v[144:147], v[140:143], v[16:19], v[144:147]
	v_mfma_f32_16x16x32_bf16 v[148:151], v[140:143], v[32:35], v[148:151]
	v_add_f32_e32 v43, 1.0, v43
	v_mul_f32_e32 v41, v109, v41
	v_rcp_f32_e32 v109, v38
	v_mul_f32_e32 v38, v42, v160
	v_exp_f32_e32 v38, v38
	v_mul_f32_e32 v41, v41, v108
	v_exp_f32_e32 v39, v39
	v_fma_f32 v42, -v38, v38, 1.0
	v_max_f32_e32 v42, 0, v42
	v_rcp_f32_e32 v43, v43
	v_sqrt_f32_e32 v42, v42
	s_nop 0
	s_waitcnt lgkmcnt(0)
	v_lshlrev_b32_e32 v108, 16, v155
	v_add_f32_e32 v39, 1.0, v39
	s_waitcnt lgkmcnt(0)
	v_lshlrev_b32_e32 v105, 16, v156
	s_nop 1
	s_nop 1
	v_mul_f32_e32 v42, v109, v42
	v_mul_f32_e32 v42, v42, v108
	v_rcp_f32_e32 v108, v39
	v_mul_f32_e32 v39, v43, v160
	v_exp_f32_e32 v39, v39
	s_nop 0
	v_fma_f32 v43, -v39, v39, 1.0
	v_max_f32_e32 v43, 0, v43
	s_nop 0
	v_sqrt_f32_e32 v43, v43
	s_nop 0
	s_nop 0
	s_nop 0
	s_nop 1
	s_nop 1
	v_mul_f32_e32 v43, v108, v43
	v_mul_f32_e32 v43, v43, v105
	s_and_b64 vcc, exec, s[8:9]
	s_cbranch_vccnz .LBB0_144
	v_fma_f32 v108, v38, v43, v42
	v_mul_f32_e32 v109, v38, v39
	v_fma_f32 v111, v37, v108, v41
	v_mul_f32_e32 v110, v37, v109
	v_fma_f32 v112, v36, v111, v40
	v_mul_f32_e32 v105, v36, v110
	s_mov_b64 s[2:3], 0

; __device__ __forceinline__ float bf2f(bf16_t b) { return __uint_as_float(((unsigned)b) << 16); }
; __device__ __forceinline__ float sigmoidf(float z) { return __builtin_amdgcn_rcpf(1.0f + __expf(-z)); }
; __device__ void lru_fused_phase(const int bid, const int nblk, bf16_t* __restrict__ U, bf16_t* __restrict__ HF, const bf16_t* __restrict__ Wg, const float* __restrict__ cw, const float* __restrict__ cb, ...
;     ...
; #pragma unroll
;                     for (int j = 0; j < 4; ++j) {
;                         const float c = bf2f(*(const unsigned short*)(buf + (16 * rt + 4 * fq + j) * RS + chl * 2));
;                         const float r = sigmoidf(za[j] + ba), ig = sigmoidf(zi[j] + bi_);
;                         const float la = -sp * r;
;                         av[j] = __expf(la);
;                         bv[j] = __builtin_sqrtf(fmaxf(1.0f - av[j] * av[j], 0.f)) * ig * c;
;                     }
.LBB0_165:
	s_mov_b64 s[2:3], -1
	s_waitcnt lgkmcnt(1)
	s_waitcnt lgkmcnt(0)
	s_waitcnt lgkmcnt(0)
	v_or_b32_e32 v106, s38, v46
	v_mad_u32_u24 v106, v106, s35, v10
	s_waitcnt lgkmcnt(0)
	v_or_b32_e32 v152, s70, v47
	v_xor_b32_e32 v152, 48, v152
	v_mad_u32_u24 v152, v152, s35, v104
	ds_read_b128 v[128:131], v152
	ds_read_b128 v[132:135], v152 offset:64
	ds_read_b128 v[136:139], v152 offset:128
	ds_read_b128 v[140:143], v152 offset:192
	ds_read_u16 v153, v106
	ds_read_u16 v154, v106 offset:272
	ds_read_u16 v155, v106 offset:544
	ds_read_u16 v156, v106 offset:816
	v_fmamk_f32 v40, v144, 0xbfb8aa3b, v157
	v_exp_f32_e32 v40, v40
	v_fmamk_f32 v41, v145, 0xbfb8aa3b, v157
	v_exp_f32_e32 v41, v41
	s_nop 2
	v_fmamk_f32 v36, v148, 0xbfb8aa3b, v127
	v_add_f32_e32 v40, 1.0, v40
	v_exp_f32_e32 v36, v36
	v_rcp_f32_e32 v40, v40
	v_fmamk_f32 v37, v149, 0xbfb8aa3b, v127
	v_add_f32_e32 v36, 1.0, v36
	v_rcp_f32_e32 v109, v36
	v_mul_f32_e32 v36, v40, v160
	v_exp_f32_e32 v36, v36
	v_add_f32_e32 v41, 1.0, v41
	v_exp_f32_e32 v37, v37
	v_rcp_f32_e32 v41, v41
	v_fma_f32 v40, -v36, v36, 1.0
	v_max_f32_e32 v40, 0, v40
	v_add_f32_e32 v37, 1.0, v37
	v_sqrt_f32_e32 v40, v40
	s_nop 0
	v_fmamk_f32 v42, v146, 0xbfb8aa3b, v157
	v_exp_f32_e32 v42, v42
	v_fmamk_f32 v38, v150, 0xbfb8aa3b, v127
	v_add_f32_e32 v42, 1.0, v42
	v_exp_f32_e32 v38, v38
	v_rcp_f32_e32 v42, v42
	v_mul_f32_e32 v40, v109, v40
	v_rcp_f32_e32 v109, v37
	v_mul_f32_e32 v37, v41, v160
	v_exp_f32_e32 v37, v37
	v_add_f32_e32 v38, 1.0, v38
	v_fmamk_f32 v43, v147, 0xbfb8aa3b, v157
	v_fma_f32 v41, -v37, v37, 1.0
	v_max_f32_e32 v41, 0, v41
	s_waitcnt lgkmcnt(0)
	v_lshlrev_b32_e32 v108, 16, v153
	v_sqrt_f32_e32 v41, v41
	s_nop 0
	v_mul_f32_e32 v40, v40, v108
	v_exp_f32_e32 v43, v43
	s_waitcnt lgkmcnt(0)
	v_lshlrev_b32_e32 v108, 16, v154
	v_fmamk_f32 v39, v151, 0xbfb8aa3b, v127
	s_waitcnt lgkmcnt(0)
	v_mfma_f32_16x16x32_bf16 v[144:147], v[128:131], v[0:3], 0
	v_mfma_f32_16x16x32_bf16 v[148:151], v[128:131], v[20:23], 0
	v_mfma_f32_16x16x32_bf16 v[144:147], v[132:135], v[4:7], v[144:147]
	v_mfma_f32_16x16x32_bf16 v[148:151], v[132:135], v[24:27], v[148:151]
	v_mfma_f32_16x16x32_bf16 v[144:147], v[136:139], v[12:15], v[144:147]
	v_mfma_f32_16x16x32_bf16 v[148:151], v[136:139], v[28:31], v[148:151]
	v_mfma_f32_16x16x32_bf16 v[144:147], v[140:143], v[16:19], v[144:147]
	v_mfma_f32_16x16x32_bf16 v[148:151], v[140:143], v[32:35], v[148:151]
	v_add_f32_e32 v43, 1.0, v43
	v_mul_f32_e32 v41, v109, v41
	v_rcp_f32_e32 v109, v38
	v_mul_f32_e32 v38, v42, v160
	v_exp_f32_e32 v38, v38
	v_mul_f32_e32 v41, v41, v108
	v_exp_f32_e32 v39, v39
	v_fma_f32 v42, -v38, v38, 1.0
	v_max_f32_e32 v42, 0, v42
	v_rcp_f32_e32 v43, v43
	v_sqrt_f32_e32 v42, v42
	s_nop 0
	s_waitcnt lgkmcnt(0)
	v_lshlrev_b32_e32 v108, 16, v155
	v_add_f32_e32 v39, 1.0, v39
	s_waitcnt lgkmcnt(0)
	v_lshlrev_b32_e32 v106, 16, v156
	s_nop 1
	s_nop 1
	v_mul_f32_e32 v42, v109, v42
	v_mul_f32_e32 v42, v42, v108
	v_rcp_f32_e32 v108, v39
	v_mul_f32_e32 v39, v43, v160
	v_exp_f32_e32 v39, v39
	s_nop 0
	v_fma_f32 v43, -v39, v39, 1.0
	v_max_f32_e32 v43, 0, v43
	s_nop 0
	v_sqrt_f32_e32 v43, v43
	s_nop 0
	s_nop 0
	s_nop 0
	s_nop 1
	s_nop 1
	v_mul_f32_e32 v43, v108, v43
	v_mul_f32_e32 v43, v43, v106
	s_and_b64 vcc, exec, s[8:9]
	s_cbranch_vccnz .LBB0_167
	v_fma_f32 v108, v38, v43, v42
	v_mul_f32_e32 v109, v38, v39
	v_fma_f32 v111, v37, v108, v41
	v_mul_f32_e32 v110, v37, v109
	v_fma_f32 v112, v36, v111, v40
	v_mul_f32_e32 v106, v36, v110
	s_mov_b64 s[2:3], 0

; __device__ __forceinline__ float bf2f(bf16_t b) { return __uint_as_float(((unsigned)b) << 16); }
; __device__ __forceinline__ float sigmoidf(float z) { return __builtin_amdgcn_rcpf(1.0f + __expf(-z)); }
; __device__ void lru_fused_phase(const int bid, const int nblk, bf16_t* __restrict__ U, bf16_t* __restrict__ HF, const bf16_t* __restrict__ Wg, const float* __restrict__ cw, const float* __restrict__ cb, ...
;     ...
; #pragma unroll
;                     for (int j = 0; j < 4; ++j) {
;                         const float c = bf2f(*(const unsigned short*)(buf + (16 * rt + 4 * fq + j) * RS + chl * 2));
;                         const float r = sigmoidf(za[j] + ba), ig = sigmoidf(zi[j] + bi_);
;                         const float la = -sp * r;
;                         av[j] = __expf(la);
;                         bv[j] = __builtin_sqrtf(fmaxf(1.0f - av[j] * av[j], 0.f)) * ig * c;
;                     }
.LBB0_188:
	s_mov_b64 s[2:3], -1
	s_waitcnt lgkmcnt(1)
	s_waitcnt lgkmcnt(0)
	s_waitcnt lgkmcnt(0)
	v_or_b32_e32 v104, s38, v46
	v_mad_u32_u24 v104, v104, s35, v10
	ds_read_u16 v10, v104
	s_waitcnt lgkmcnt(1)
	s_waitcnt lgkmcnt(0)
	v_lshlrev_b32_e32 v105, 16, v10
	s_nop 5
	ds_read_u16 v154, v104 offset:272
	ds_read_u16 v155, v104 offset:544
	ds_read_u16 v156, v104 offset:816
	v_fmamk_f32 v10, v144, 0xbfb8aa3b, v157
	v_exp_f32_e32 v10, v10
	v_fmamk_f32 v41, v145, 0xbfb8aa3b, v157
	v_add_f32_e32 v10, 1.0, v10
	v_rcp_f32_e32 v10, v10
	v_exp_f32_e32 v41, v41
	s_nop 2
	v_fmamk_f32 v36, v148, 0xbfb8aa3b, v127
	v_mul_f32_e32 v10, v10, v160
	v_exp_f32_e32 v10, v10
	v_exp_f32_e32 v36, v36
	v_fmamk_f32 v37, v149, 0xbfb8aa3b, v127
	v_fma_f32 v40, -v10, v10, 1.0
	v_max_f32_e32 v40, 0, v40
	v_add_f32_e32 v36, 1.0, v36
	v_sqrt_f32_e32 v40, v40
	s_nop 0
	v_rcp_f32_e32 v36, v36
	v_add_f32_e32 v41, 1.0, v41
	v_exp_f32_e32 v37, v37
	v_rcp_f32_e32 v41, v41
	v_add_f32_e32 v37, 1.0, v37
	v_fmamk_f32 v42, v146, 0xbfb8aa3b, v157
	v_exp_f32_e32 v42, v42
	v_mul_f32_e32 v36, v36, v40
	v_mul_f32_e32 v36, v36, v105
	v_rcp_f32_e32 v105, v37
	v_mul_f32_e32 v37, v41, v160
	v_exp_f32_e32 v37, v37
	v_fmamk_f32 v38, v150, 0xbfb8aa3b, v127
	v_add_f32_e32 v42, 1.0, v42
	v_fma_f32 v41, -v37, v37, 1.0
	v_max_f32_e32 v41, 0, v41
	v_exp_f32_e32 v38, v38
	v_sqrt_f32_e32 v41, v41
	s_nop 0
	v_rcp_f32_e32 v42, v42
	v_add_f32_e32 v38, 1.0, v38
	v_fmamk_f32 v43, v147, 0xbfb8aa3b, v157
	v_exp_f32_e32 v43, v43
	s_waitcnt lgkmcnt(0)
	v_lshlrev_b32_e32 v40, 16, v154
	v_fmamk_f32 v39, v151, 0xbfb8aa3b, v127
	v_mul_f32_e32 v41, v105, v41
	v_rcp_f32_e32 v105, v38
	v_mul_f32_e32 v38, v42, v160
	v_exp_f32_e32 v38, v38
	v_mul_f32_e32 v40, v41, v40
	v_fma_f32 v42, -v38, v38, 1.0
	v_max_f32_e32 v42, 0, v42
	v_add_f32_e32 v43, 1.0, v43
	v_sqrt_f32_e32 v42, v42
	s_nop 0
	v_exp_f32_e32 v39, v39
	v_rcp_f32_e32 v43, v43
	s_waitcnt lgkmcnt(0)
	v_lshlrev_b32_e32 v41, 16, v155
	v_add_f32_e32 v39, 1.0, v39
	s_nop 1
	s_nop 1
	v_mul_f32_e32 v42, v105, v42
	v_mul_f32_e32 v41, v42, v41
	v_rcp_f32_e32 v104, v39
	v_mul_f32_e32 v39, v43, v160
	v_exp_f32_e32 v39, v39
	s_waitcnt lgkmcnt(0)
	v_lshlrev_b32_e32 v42, 16, v156
	v_fma_f32 v43, -v39, v39, 1.0
	v_max_f32_e32 v43, 0, v43
	s_nop 0
	v_sqrt_f32_e32 v43, v43
	s_nop 0
	s_nop 0
	s_nop 0
	s_nop 1
	s_nop 1
	v_mul_f32_e32 v43, v104, v43
	v_mul_f32_e32 v42, v43, v42
	s_and_b64 vcc, exec, s[8:9]
	s_cbranch_vccnz .LBB0_190
	v_fma_f32 v43, v38, v42, v41
	v_mul_f32_e32 v104, v38, v39
	v_fma_f32 v108, v37, v43, v40
	v_mul_f32_e32 v107, v37, v104
	v_fma_f32 v109, v10, v108, v36
	v_mul_f32_e32 v105, v10, v107
	s_mov_b64 s[2:3], 0
